# weight-prep phase: descending item order selected by bit 3 of the workgroup index (alternates within each XCD) instead of bit 0
# baseline (speedup 1.0000x reference)
.LBB0_17:
	s_or_b64 exec, exec, s[4:5]
	s_load_dwordx4 s[72:75], s[0:1], 0x80
	s_load_dwordx16 s[36:51], s[0:1], 0x0
	s_cmpk_gt_i32 s85, 0x280
	v_mbcnt_lo_u32_b32 v0, -1, 0
	v_mbcnt_hi_u32_b32 v0, -1, v0
	s_waitcnt lgkmcnt(0)
	v_writelane_b32 v254, s36, 16
	s_nop 1
	v_writelane_b32 v254, s37, 17
	v_writelane_b32 v254, s38, 18
	v_writelane_b32 v254, s39, 19
	v_writelane_b32 v254, s40, 20
	v_writelane_b32 v254, s41, 21
	v_writelane_b32 v254, s42, 22
	v_writelane_b32 v254, s43, 23
	v_writelane_b32 v254, s44, 24
	v_writelane_b32 v254, s45, 25
	v_writelane_b32 v254, s46, 26
	v_writelane_b32 v254, s47, 27
	v_writelane_b32 v254, s48, 28
	v_writelane_b32 v254, s49, 29
	v_writelane_b32 v254, s50, 30
	v_writelane_b32 v254, s51, 31
	s_cbranch_scc1 .LBB0_51
	s_add_u32 s6, s28, 0x1e40000
	v_add_u32_e32 v16, s3, v0
	s_addc_u32 s7, s29, 0
	v_and_b32_e32 v0, 15, v0
	s_add_u32 s8, s28, 0x2179000
	v_cvt_f32_ubyte0_e32 v0, v0
	s_addc_u32 s9, s29, 0
	v_mul_f32_e32 v0, 0xbd800000, v0
	s_add_u32 s10, s28, 0x1a00000
	v_mul_f32_e32 v0, 0x41549a78, v0
	s_addc_u32 s11, s29, 0
	v_exp_f32_e32 v17, v0
	s_add_u32 s12, s28, 0x1200000
	s_movk_i32 s0, 0x400
	s_addc_u32 s13, s29, 0
	s_lshl_b32 s4, s16, 2
	s_mov_b32 s56, 0x54442d18
	v_cmp_gt_i32_e64 s[0:1], s0, v16
	s_and_b32 s14, s4, 0xffffff00
	s_movk_i32 s15, 0x1400
	s_movk_i32 s17, 0x3ff
	s_movk_i32 s18, 0xfc00
	v_mov_b32_e32 v1, 0
	s_movk_i32 s19, 0x11ff
	s_mov_b32 s35, 0
	s_movk_i32 s20, 0x3000
	s_movk_i32 s21, 0x6000
	s_mov_b32 s22, 0x9000
	s_mov_b32 s23, 0xc000
	s_mov_b32 s24, 0xf000
	s_mov_b32 s25, 0x12000
	s_mov_b32 s26, 0x15000
	s_movk_i32 s27, 0x500
	s_movk_i32 s33, 0x140
	s_mov_b32 s57, 0x401921fb
	s_mov_b32 s59, 0xc01921fb
	s_movk_i32 s60, 0x1ff
	s_movk_i32 s61, 0xfc
	s_mov_b32 s62, 0x10100
	s_mov_b32 s63, 0x38e38e39
	s_movk_i32 s64, 0x2400
	v_mov_b32_e32 v18, 4
	v_mov_b32_e32 v19, 2
	v_mov_b32_e32 v20, 6
	s_mov_b32 s65, s85
	s_mov_b32 s97, s30
	s_bitcmp1_b32 s85, 3
	s_cbranch_scc0 .Lp0_asc
	s_add_i32 s65, s85, 0x200
	s_cmpk_gt_i32 s65, 0x280
	s_cbranch_scc0 .Lp0_d1
	s_add_i32 s65, s65, 0xffffff00
